# next-phase weight touch in the barrier shadow (C->D, D->E, E->F): parked waves read the first two K-tiles of the next weight tile
# speedup vs baseline: 1.0071x; 1.0071x over previous
;     __device__ __forceinline__ bool next_(int i, GUnit& u) const {
;     ...
;         } else if (phase == PH_D) {
;             if (i >= 1 || c >= 256) return false;
;             int pm, pn; pg8::tile_order(64, 4, c, pm, pn); u.pm = pm; u.pn = pn; u.K = 1024;
;             u.A = w + B_MRG + (size_t)pm * 256 * 1024 * 2; u.B = w + W_MIX + (size_t)pn * 256 * 1024 * 2; u.kind = K_MIX; return true;
;         } else if (phase == PH_E) {
;             if (c >= 128 && i < 2) { int pm, pn; pg8::tile_order(64, 4, c, pm, pn); pn = 2 * (pn - 2) + i; u.pm = pm; u.pn = pn;
;                 u.K = 256; u.A = w + WS_P16 + (size_t)pm * 256 * 256 * 2; u.B = w + W_P + (size_t)pn * 256 * 256 * 2; u.kind = K_PP;
;                 return true; }
;             const int L = (c >= 128 ? i - 2 : i) * G + c; if (L >= 1408) return false;
;             int pm, pn; pg8::tile_order(64, 22, L, pm, pn); u.pm = pm; u.pn = pn; u.K = 1024;
;             u.A = w + WS_H16 + (size_t)pm * 256 * 1024 * 2; u.B = w + W_UP + (size_t)pn * 128 * 1024 * 2; u.bhs = (size_t)DFF * 1024 * 2; u.kind = K_FFN; return true;
;         } else {
;             if (i >= 2 || c >= 256) return false;
;             int pm, pn; pg8::tile_order(64, 4, c, pm, pn); u.pm = pm; u.pn = pn;
;             if (i == 0) { u.K = 1024; u.A = w + WS_H16 + (size_t)pm * 256 * 1024 * 2; u.B = w + (par ? W_G2 : W_G) + (size_t)pn * 256 * 1024 * 2; u.kind = K_PG; return true; }
;             u.K = DFF; u.A = w + B_VAL + (size_t)pm * 256 * DFF * 2; u.B = w + (par ? W_D2 : W_D) + (size_t)pn * 256 * DFF * 2; u.kind = K_DOWN; return true;
;         }
.Ltch_full:
	s_cmp_eq_u32 s91, 3
	s_cbranch_scc1 .Ltch_d_a
	s_cmp_eq_u32 s91, 4
	s_cbranch_scc1 .Ltch_e_a
	s_cmp_eq_u32 s91, 6
	s_cbranch_scc1 .Ltch_f_a
	s_branch .LBB0_763
.Ltch_d_a:
	v_readlane_b32 s6, v252, 57
	v_readlane_b32 s7, v252, 58
	s_mov_b32 s8, 11
	s_mov_b32 s9, 0
	s_branch .Ltch_go_a
.Ltch_e_a:
	v_readlane_b32 s4, v251, 30
	s_mov_b32 s9, 0
	s_cmp_lg_u32 s4, 0
	s_cbranch_scc1 .Ltch_epp_a
	v_readlane_b32 s6, v251, 39
	v_readlane_b32 s7, v251, 40
	s_mov_b32 s8, 11
	s_mov_b32 s9, 0x540000
	s_branch .Ltch_go_a
.Ltch_epp_a:
	v_readlane_b32 s6, v253, 29
	v_readlane_b32 s7, v253, 30
	s_mov_b32 s8, 9
	s_branch .Ltch_go_a
.Ltch_f_a:
	v_readlane_b32 s6, v253, 8
	v_readlane_b32 s7, v253, 9
	s_and_b32 s4, s72, 1
	s_mov_b32 s5, 0x2100000
	s_cmp_eq_u32 s4, 0
	s_cselect_b32 s4, s5, 0x13200000
	s_add_u32 s6, s6, s4
	s_addc_u32 s7, s7, 0
	s_mov_b32 s8, 11
	s_mov_b32 s9, 0
.Ltch_go_a:
	v_readlane_b32 s5, v254, 6
	v_mbcnt_lo_u32_b32 v245, -1, 0
	v_mbcnt_hi_u32_b32 v245, -1, v245
	s_add_i32 s5, s5, -1
	s_lshl_b32 s5, s5, 6
	v_mov_b32_e32 v248, s9
	v_add_u32_e32 v245, s5, v245
	v_lshrrev_b32_e32 v246, 1, v245
	v_and_b32_e32 v247, 1, v245
	v_cmp_lt_u32_e32 vcc, 0x7f, v246
	v_lshlrev_b32_e32 v246, s8, v246
	v_lshl_add_u32 v246, v247, 7, v246
	v_cndmask_b32_e32 v247, 0, v248, vcc
	v_add_u32_e32 v246, v246, v247
	s_nop 0
	global_load_dword v244, v246, s[6:7]
	v_cmp_gt_u32_e32 vcc, 64, v245
	s_and_saveexec_b64 s[4:5], vcc
	s_cbranch_execz .Ltch_end_a
	v_add_u32_e32 v245, 0x1c0, v245
	v_lshrrev_b32_e32 v246, 1, v245
	v_and_b32_e32 v247, 1, v245
	v_lshlrev_b32_e32 v246, s8, v246
	v_lshl_add_u32 v246, v247, 7, v246
	v_add_u32_e32 v246, v246, v248
	s_nop 0
	global_load_dword v244, v246, s[6:7]
.Ltch_end_a:
	s_or_b64 exec, exec, s[4:5]
	s_branch .LBB0_763

; __device__ __forceinline__ void xcd_barrier_arrive(const XcdBarrier& b) {
;     ...
;             b.st[2] = tgt;
;         }
;         asm volatile("s_waitcnt vmcnt(0) lgkmcnt(0)" ::: "memory");
;     }
.LBB0_776:
	s_or_b64 exec, exec, s[2:3]
	s_waitcnt vmcnt(0) lgkmcnt(0)
	s_branch .LBB0_777
